# skinny GEMM epilogue (mix too): residual-row and gain/bias loads hoisted ahead of the statistics loads
# speedup vs baseline: 1.0129x; 1.0020x over previous
; #define LAS __attribute__((address_space(3)))
; template <int KSPLIT, class F>
; __device__ __forceinline__ void skinny_gemm(const bf16_t* A, const bf16_t* Bt, int N, int K, const F& f, LAS unsigned char* lds, int bx, int G, int wave) {
;     ...
;     for (int t = bx; t < ntiles; t += G) {
;         const int rg = t % RG, n0 = (t / RG) * 16;
;         const int mt = rg * MTW + (wave % MTW), kq = wave / MTW;
;         const bf16_t* ap = A + (size_t)(MP + 16 * mt + fr) * K + kq * klen + 8 * fq;
;         const bf16_t* bp = Bt + (size_t)(n0 + fr) * K + kq * klen + 8 * fq;
;         f32x4 acc = (f32x4){0.f, 0.f, 0.f, 0.f};
; #pragma unroll 16
;         for (int k = 0; k < klen; k += 32) {
;             const bf16x8 af = *(const bf16x8*)(ap + k), bf = *(const bf16x8*)(bp + k);
;             acc = __builtin_amdgcn_mfma_f32_16x16x32_bf16(bf, af, acc, 0, 0, 0);
;         }
;         if (KSPLIT > 1) {
;             __syncthreads();
;             *(LAS f32x4*)(lds + wave * 1024 + lane * 16) = acc;
;             __syncthreads();
;             if (kq == 0) {
; #pragma unroll
.LBB0_1948:
	s_ashr_i32 s0, s4, 31
	s_lshr_b32 s0, s0, 30
	s_add_i32 s0, s4, s0
	s_ashr_i32 s8, s0, 2
	s_lshl_b32 s1, s8, 7
	v_subrev_u32_e32 v24, s1, v39
	v_add_u32_e32 v4, 0x4000, v24
	v_mov_b32_e32 v5, v2
	s_lshl_b32 s0, s8, 4
	v_lshlrev_b64 v[4:5], 11, v[4:5]
	v_lshl_add_u64 v[16:17], v[0:1], 0, v[4:5]
	v_or_b32_e32 v4, s0, v3
	v_ashrrev_i32_e32 v5, 31, v4
	v_lshlrev_b64 v[4:5], 11, v[4:5]
	v_lshl_add_u64 v[18:19], v[20:21], 0, v[4:5]
	s_waitcnt lgkmcnt(0)
	v_readlane_b32 s10, v253, 39
	v_readlane_b32 s11, v253, 40
	s_andn2_b64 vcc, exec, s[10:11]
	v_readlane_b32 s100, v251, 60
	s_mul_i32 s100, s100, 0x3000
	s_add_i32 s100, s100, 0x2000
	v_lshrrev_b32_e32 v202, 2, v219
	v_and_b32_e32 v203, 15, v219
	v_lshrrev_b32_e32 v201, 4, v219
	v_sub_u32_e32 v202, v202, v203
	v_lshlrev_b32_e32 v202, 11, v202
	v_and_b32_e32 v204, 3, v219
	v_xor_b32_e32 v204, v204, v201
	v_sub_u32_e32 v204, v204, v201
	v_lshl_add_u32 v202, v204, 4, v202
	v_lshrrev_b32_e32 v204, 2, v203
	v_xor_b32_e32 v204, v204, v201
	v_lshlrev_b32_e32 v200, 6, v203
	v_lshl_add_u32 v200, v204, 4, v200
	v_add_u32_e32 v200, s100, v200
	v_ashrrev_i32_e32 v203, 31, v202
	v_lshl_add_u64 v[196:197], v[202:203], 0, v[16:17]
	v_lshl_add_u64 v[198:199], v[202:203], 0, v[18:19]
	s_add_i32 m0, s100, 0
	s_nop 0
	global_load_lds_dwordx4 v[196:197], off
	s_add_i32 m0, s100, 1024
	s_nop 0
	global_load_lds_dwordx4 v[198:199], off
	s_add_i32 m0, s100, 1984
	s_nop 0
	global_load_lds_dwordx4 v[196:197], off offset:64
	s_add_i32 m0, s100, 3008
	s_nop 0
	global_load_lds_dwordx4 v[198:199], off offset:64
	s_add_i32 m0, s100, 3968
	s_nop 0
	global_load_lds_dwordx4 v[196:197], off offset:128
	s_add_i32 m0, s100, 4992
	s_nop 0
	global_load_lds_dwordx4 v[198:199], off offset:128
	s_add_i32 m0, s100, 5952
	s_nop 0
	global_load_lds_dwordx4 v[196:197], off offset:192
	s_add_i32 m0, s100, 6976
	s_nop 0
	global_load_lds_dwordx4 v[198:199], off offset:192
	s_add_i32 m0, s100, 7936
	s_nop 0
	global_load_lds_dwordx4 v[196:197], off offset:256
	s_add_i32 m0, s100, 8960
	s_nop 0
	global_load_lds_dwordx4 v[198:199], off offset:256
	s_add_i32 m0, s100, 9920
	s_nop 0
	global_load_lds_dwordx4 v[196:197], off offset:320
	s_add_i32 m0, s100, 10944
	s_nop 0
	global_load_lds_dwordx4 v[198:199], off offset:320
	s_waitcnt vmcnt(10)
	ds_read_b128 v[180:183], v200 offset:0
	ds_read_b128 v[184:187], v200 offset:1024
	s_waitcnt vmcnt(8)
	ds_read_b128 v[188:191], v200 offset:2048
	ds_read_b128 v[192:195], v200 offset:3072
	s_waitcnt lgkmcnt(2)
	v_mfma_f32_16x16x32_bf16 v[4:7], v[184:187], v[180:183], 0
	s_add_i32 m0, s100, -384
	s_nop 0
	global_load_lds_dwordx4 v[196:197], off offset:384
	s_add_i32 m0, s100, 640
	s_nop 0
	global_load_lds_dwordx4 v[198:199], off offset:384
	s_waitcnt vmcnt(8)
	ds_read_b128 v[180:183], v200 offset:4096
	ds_read_b128 v[184:187], v200 offset:5120
	s_waitcnt lgkmcnt(2)
	v_mfma_f32_16x16x32_bf16 v[4:7], v[192:195], v[188:191], v[4:7]
	s_add_i32 m0, s100, 1600
	s_nop 0
	global_load_lds_dwordx4 v[196:197], off offset:448
	s_add_i32 m0, s100, 2624
	s_nop 0
	global_load_lds_dwordx4 v[198:199], off offset:448
	s_waitcnt vmcnt(8)
	ds_read_b128 v[188:191], v200 offset:6144
	ds_read_b128 v[192:195], v200 offset:7168
	s_waitcnt lgkmcnt(2)
	v_mfma_f32_16x16x32_bf16 v[4:7], v[184:187], v[180:183], v[4:7]
	s_waitcnt vmcnt(6)
	ds_read_b128 v[180:183], v200 offset:8192
	ds_read_b128 v[184:187], v200 offset:9216
	s_waitcnt lgkmcnt(2)
	v_mfma_f32_16x16x32_bf16 v[4:7], v[192:195], v[188:191], v[4:7]
	s_waitcnt vmcnt(4)
	ds_read_b128 v[188:191], v200 offset:10240
	ds_read_b128 v[192:195], v200 offset:11264
	s_waitcnt lgkmcnt(2)
	v_mfma_f32_16x16x32_bf16 v[4:7], v[184:187], v[180:183], v[4:7]
	s_waitcnt vmcnt(2)
	ds_read_b128 v[180:183], v200 offset:0
	ds_read_b128 v[184:187], v200 offset:1024
	s_waitcnt lgkmcnt(2)
	v_mfma_f32_16x16x32_bf16 v[4:7], v[192:195], v[188:191], v[4:7]
	s_waitcnt vmcnt(0)
	ds_read_b128 v[188:191], v200 offset:2048
	ds_read_b128 v[192:195], v200 offset:3072
	s_waitcnt lgkmcnt(2)
	v_mfma_f32_16x16x32_bf16 v[4:7], v[184:187], v[180:183], v[4:7]
	s_waitcnt lgkmcnt(0)
	s_barrier
	v_mfma_f32_16x16x32_bf16 v[4:7], v[192:195], v[188:191], v[4:7]
	s_nop 7
	ds_write_b128 v41, v[4:7]
	s_waitcnt lgkmcnt(0)
	s_barrier
	s_cbranch_vccnz .LBB0_1947
	ds_read_b128 v[16:19], v41 offset:2048
	ds_read_b128 v[12:15], v41 offset:4096
	ds_read_b128 v[8:11], v41 offset:6144
	v_cndmask_b32_e64 v25, 0, 1, s[96:97]
	v_cmp_ne_u32_e64 s[40:41], 1, v25
	s_andn2_b64 vcc, exec, s[96:97]
	v_ashrrev_i32_e32 v25, 31, v24
	s_cbranch_vccnz .LBB0_1951
; __device__ __forceinline__ u32x2 pk4(f32x4 v) { u32x2 r; r.x = pk2(v.x, v.y); r.y = pk2(v.z, v.w); return r; }
; __device__ __forceinline__ void stats_sk(const float* sts, int row, int fq, float& mu, float& rs) {
;     const f32x4* p = (const f32x4*)(sts + (size_t)(row - MP) * 128 + fq * 32);
;     float s1 = 0.f, s2 = 0.f;
; #pragma unroll
;     for (int i = 0; i < 8; ++i) { const f32x4 a = p[i]; s1 += a.x + a.z; s2 += a.y + a.w; }
;     s1 += __shfl_xor(s1, 16); s2 += __shfl_xor(s2, 16); s1 += __shfl_xor(s1, 32); s2 += __shfl_xor(s2, 32);
;     mu = s1 * (1.f / DM); rs = __builtin_amdgcn_rsqf(fmaxf(s2 * (1.f / DM) - mu * mu, 0.f) + LN_EPS);
;     __device__ __forceinline__ void sk(int row, int col, f32x4 v, int fq) const {
;         float mu = 0.f, rs = 1.f; if (ln) stats_sk(sts_p, row, fq, mu, rs);
;         const u32x2 raw = *(const u32x2*)(src + (size_t)row * DM + col);
;         f32x4 x = (f32x4){bflo(raw.x), bfhi(raw.x), bflo(raw.y), bfhi(raw.y)};
;         if (ln) x = (x - mu) * rs * *(const f32x4*)(g + col) + *(const f32x4*)(b + col);
;         const u32x2 pz = pk4(x * ALPHA + v);
;         *(u32x2*)(dst + (size_t)row * DM + col) = pz;
;         const float z0 = bflo(pz.x), z1 = bfhi(pz.x), z2 = bflo(pz.y), z3 = bfhi(pz.y);
;         float s1 = (z0 + z1) + (z2 + z3), s2 = (z0 * z0 + z1 * z1) + (z2 * z2 + z3 * z3);
;         s1 += __shfl_xor(s1, 16); s2 += __shfl_xor(s2, 16); s1 += __shfl_xor(s1, 32); s2 += __shfl_xor(s2, 32);
;         if (fq == 0) { float* p = sts_n + (size_t)(row - MP) * 128 + (col >> 4) * 2; p[0] = s1; p[1] = s2; }
	v_add_u32_e32 v192, s0, v38
	s_lshl_b32 s101, s8, 17
	v_subrev_u32_e32 v180, s101, v40
	v_mov_b32_e32 v181, v2
	v_lshl_add_u64 v[180:181], v[180:181], 1, s[46:47]
	v_ashrrev_i32_e32 v193, 31, v192
	v_lshl_add_u64 v[180:181], v[192:193], 1, v[180:181]
	global_load_dwordx2 v[182:183], v[180:181], off
	v_lshlrev_b64 v[192:193], 2, v[192:193]
	v_readlane_b32 s101, v251, 34
	s_nop 1
	v_mov_b32_e32 v184, s101
	v_readlane_b32 s101, v251, 35
	s_nop 1
	v_mov_b32_e32 v185, s101
	v_lshl_add_u64 v[184:185], v[184:185], 0, v[192:193]
	v_readlane_b32 s101, v251, 36
	s_nop 1
	v_mov_b32_e32 v188, s101
	v_readlane_b32 s101, v251, 37
	s_nop 1
	v_mov_b32_e32 v189, s101
	v_lshl_add_u64 v[188:189], v[188:189], 0, v[192:193]
	global_load_dwordx4 v[184:187], v[184:185], off
	s_nop 0
	global_load_dwordx4 v[188:191], v[188:189], off
	v_lshlrev_b64 v[26:27], 9, v[24:25]
	v_lshl_add_u64 v[54:55], v[22:23], 0, v[26:27]
	global_load_dwordx4 v[42:45], v[54:55], off offset:48
	global_load_dwordx4 v[26:29], v[54:55], off offset:32
	global_load_dwordx4 v[46:49], v[54:55], off offset:16
	global_load_dwordx4 v[30:33], v[54:55], off
	s_waitcnt vmcnt(1)
	v_add_f32_e32 v34, v47, v49
	s_waitcnt vmcnt(0)
	v_add_f32_e32 v36, v31, v33
	v_mov_b32_e32 v31, v46
	v_mov_b32_e32 v33, v48
	v_pk_add_f32 v[32:33], v[30:31], v[32:33]
	v_add_f32_e32 v30, v27, v29
	v_mov_b32_e32 v27, v42
	v_mov_b32_e32 v29, v44
	v_pk_add_f32 v[26:27], v[26:27], v[28:29]
	v_add_f32_e32 v28, v43, v45
	global_load_dwordx4 v[42:45], v[54:55], off offset:112
	global_load_dwordx4 v[46:49], v[54:55], off offset:96
	global_load_dwordx4 v[50:53], v[54:55], off offset:80
	s_nop 0
	global_load_dwordx4 v[54:57], v[54:55], off offset:64
	v_and_b32_e32 v31, 64, v219
	v_xor_b32_e32 v29, 16, v219
	v_add_u32_e32 v31, 64, v31
	v_cmp_lt_i32_e32 vcc, v29, v31
	v_mov_b32_e32 v37, v32
	v_pk_add_f32 v[36:37], v[36:37], 0 op_sel_hi:[1,0]
	v_cndmask_b32_e32 v29, v219, v29, vcc
	v_mov_b32_e32 v35, v33
	v_pk_add_f32 v[32:33], v[36:37], v[34:35]
	s_waitcnt vmcnt(0)
	v_add_f32_e32 v58, v55, v57
	v_mov_b32_e32 v57, v52
	v_add_f32_e32 v52, v47, v49
	v_mov_b32_e32 v49, v44
	v_lshlrev_b32_e32 v44, 2, v29
	v_xor_b32_e32 v29, 32, v219
	v_cmp_lt_i32_e32 vcc, v29, v31
	v_mov_b32_e32 v55, v50
	v_mov_b32_e32 v31, v26
	v_cndmask_b32_e32 v29, v219, v29, vcc
	v_pk_add_f32 v[54:55], v[54:55], v[56:57]
	v_mov_b32_e32 v47, v42
	v_add_f32_e32 v42, v43, v45
	v_lshlrev_b32_e32 v45, 2, v29
	v_pk_add_f32 v[30:31], v[32:33], v[30:31]
	v_mov_b32_e32 v29, v27
	v_pk_add_f32 v[26:27], v[30:31], v[28:29]
	v_mov_b32_e32 v59, v54
	v_add_f32_e32 v50, v51, v53
	v_pk_add_f32 v[46:47], v[46:47], v[48:49]
	v_pk_add_f32 v[26:27], v[26:27], v[58:59]
	v_mov_b32_e32 v51, v55
	v_pk_add_f32 v[26:27], v[26:27], v[50:51]
	v_mov_b32_e32 v53, v46
	v_pk_add_f32 v[26:27], v[26:27], v[52:53]
	v_mov_b32_e32 v43, v47
	v_pk_add_f32 v[26:27], v[26:27], v[42:43]
	ds_bpermute_b32 v29, v44, v27
	ds_bpermute_b32 v28, v44, v26
	s_waitcnt lgkmcnt(0)
	v_pk_add_f32 v[26:27], v[26:27], v[28:29]
	ds_bpermute_b32 v29, v45, v27
	ds_bpermute_b32 v28, v45, v26
	s_waitcnt lgkmcnt(0)
	v_pk_add_f32 v[26:27], v[26:27], v[28:29]
	s_nop 0
	v_pk_mul_f32 v[30:31], v[26:27], s[82:83] op_sel_hi:[1,0]
	s_nop 0
	v_fma_f32 v26, -v31, v31, v30
	v_max_f32_e32 v26, 0, v26
	v_add_f32_e32 v26, 0x3727c5ac, v26
	v_rsq_f32_e32 v30, v26
	s_branch .LBB0_1952
.LBB0_1951:
	v_mov_b32_e32 v30, 1.0
	v_mov_b32_e32 v31, 0
	v_add_u32_e32 v192, s0, v38
	s_lshl_b32 s101, s8, 17
	v_subrev_u32_e32 v180, s101, v40
	v_mov_b32_e32 v181, v2
	v_lshl_add_u64 v[180:181], v[180:181], 1, s[46:47]
	v_ashrrev_i32_e32 v193, 31, v192
	v_lshl_add_u64 v[180:181], v[192:193], 1, v[180:181]
	global_load_dwordx2 v[182:183], v[180:181], off
.LBB0_1952:
	v_add_u32_e32 v26, s0, v38
	s_lshl_b32 s0, s8, 17
	v_subrev_u32_e32 v28, s0, v40
	v_mov_b32_e32 v29, v2
	v_lshl_add_u64 v[32:33], v[28:29], 1, s[46:47]
	v_ashrrev_i32_e32 v27, 31, v26
	v_lshl_add_u64 v[32:33], v[26:27], 1, v[32:33]
	s_waitcnt vmcnt(0)
	v_mov_b32_e32 v34, v182
	v_mov_b32_e32 v35, v183
	s_and_b64 vcc, exec, s[40:41]
	s_waitcnt vmcnt(0)
	v_lshlrev_b32_e32 v32, 16, v34
	v_and_b32_e32 v33, 0xffff0000, v34
	v_lshlrev_b32_e32 v34, 16, v35
	v_and_b32_e32 v35, 0xffff0000, v35
	s_cbranch_vccnz .LBB0_1954
	v_readlane_b32 s48, v251, 22
	v_readlane_b32 s56, v251, 30
	v_readlane_b32 s57, v251, 31
	v_readlane_b32 s58, v251, 32
	v_readlane_b32 s59, v251, 33
	v_readlane_b32 s60, v251, 34
	v_readlane_b32 s61, v251, 35
	v_readlane_b32 s62, v251, 36
	v_readlane_b32 s63, v251, 37
	s_mov_b64 s[56:57], s[60:61]
	v_lshlrev_b64 v[36:37], 2, v[26:27]
	s_mov_b64 s[58:59], s[62:63]
	v_lshl_add_u64 v[42:43], s[58:59], 0, v[36:37]
	v_lshl_add_u64 v[36:37], s[56:57], 0, v[36:37]
	v_sub_f32_e32 v35, v35, v31
	v_sub_f32_e32 v34, v34, v31
	v_sub_f32_e32 v33, v33, v31
	v_sub_f32_e32 v32, v32, v31
	v_pk_mul_f32 v[46:47], v[30:31], v[32:33] op_sel_hi:[0,1]
	v_pk_mul_f32 v[34:35], v[30:31], v[34:35] op_sel_hi:[0,1]
	v_mov_b32_e32 v30, v184
	v_mov_b32_e32 v31, v185
	v_mov_b32_e32 v32, v186
	v_mov_b32_e32 v33, v187
	s_nop 0
	v_mov_b32_e32 v42, v188
	v_mov_b32_e32 v43, v189
	v_mov_b32_e32 v44, v190
	v_mov_b32_e32 v45, v191
	v_readlane_b32 s49, v251, 23
	v_readlane_b32 s50, v251, 24
	v_readlane_b32 s51, v251, 25
	v_readlane_b32 s52, v251, 26
	v_readlane_b32 s53, v251, 27
	v_readlane_b32 s54, v251, 28
	v_readlane_b32 s55, v251, 29
	s_waitcnt vmcnt(0)
	v_pk_fma_f32 v[34:35], v[34:35], v[32:33], v[44:45]
	v_pk_fma_f32 v[32:33], v[46:47], v[30:31], v[42:43]
